# v61 + MLA with-gain weight-conversion loops (wa, wkv_a) pipelined the same way
# baseline (speedup 1.0000x reference)
; __device__ __forceinline__ void cvt_job(const Frame& F, const float* W, int K, int Nsrc, bf16_t* dst, int nrows, int mode, float scale, const float* gain = nullptr) {
;     ...
;     for (int it = F.gw; it < nitems; it += F.NGW) {
;         const int kb = it / nblk, nb = it % nblk, k0 = 64 * kb, n0 = 32 * nb;
;         const int nsrc = map_col(mode, n0 + (lane & 31));
; #pragma unroll 8
;         for (int i = 0; i < 32; ++i) { const int kk = 2 * i + (lane >> 5); scr[kk * 33 + (lane & 31)] = (mode == MAP_ZERO) ? 0.f : W[(size_t)(k0 + kk) * Nsrc + nsrc] * (gain ? scale * gain[k0 + kk] : scale); }
.LBB0_1738:
	s_andn2_b64 vcc, exec, s[30:31]
	s_cbranch_vccnz .Lcvtga0_ng
	v_add_u32_e32 v96, s12, v6
	v_ashrrev_i32_e32 v97, 31, v96
	v_lshlrev_b64 v[98:99], 11, v[96:97]
	v_lshl_add_u64 v[100:101], v[4:5], 0, v[98:99]
	global_load_dword v152, v[100:101], off
	v_lshl_add_u64 v[102:103], v[96:97], 2, s[40:41]
	global_load_dword v153, v[102:103], off
	v_add_u32_e32 v104, 2, v96
	v_ashrrev_i32_e32 v105, 31, v104
	v_lshlrev_b64 v[106:107], 11, v[104:105]
	v_lshl_add_u64 v[108:109], v[4:5], 0, v[106:107]
	global_load_dword v154, v[108:109], off
	global_load_dword v155, v[8:9], off offset:-24
	v_add_u32_e32 v110, 4, v96
	v_ashrrev_i32_e32 v111, 31, v110
	v_lshlrev_b64 v[112:113], 11, v[110:111]
	v_lshl_add_u64 v[114:115], v[4:5], 0, v[112:113]
	global_load_dword v156, v[114:115], off
	global_load_dword v157, v[8:9], off offset:-16
	v_add_u32_e32 v116, 6, v96
	v_ashrrev_i32_e32 v117, 31, v116
	v_lshlrev_b64 v[118:119], 11, v[116:117]
	v_lshl_add_u64 v[120:121], v[4:5], 0, v[118:119]
	global_load_dword v158, v[120:121], off
	global_load_dword v159, v[8:9], off offset:-8
	v_add_u32_e32 v122, 8, v96
	v_ashrrev_i32_e32 v123, 31, v122
	v_lshlrev_b64 v[124:125], 11, v[122:123]
	v_lshl_add_u64 v[126:127], v[4:5], 0, v[124:125]
	global_load_dword v160, v[126:127], off
	global_load_dword v161, v[8:9], off
	v_add_u32_e32 v128, 10, v96
	v_ashrrev_i32_e32 v129, 31, v128
	v_lshlrev_b64 v[130:131], 11, v[128:129]
	v_lshl_add_u64 v[132:133], v[4:5], 0, v[130:131]
	global_load_dword v162, v[132:133], off
	global_load_dword v163, v[8:9], off offset:8
	v_add_u32_e32 v134, 12, v96
	v_ashrrev_i32_e32 v135, 31, v134
	v_lshlrev_b64 v[136:137], 11, v[134:135]
	v_lshl_add_u64 v[138:139], v[4:5], 0, v[136:137]
	global_load_dword v164, v[138:139], off
	global_load_dword v165, v[8:9], off offset:16
	v_add_u32_e32 v140, 14, v96
	v_ashrrev_i32_e32 v141, 31, v140
	v_lshlrev_b64 v[142:143], 11, v[140:141]
	v_lshl_add_u64 v[144:145], v[4:5], 0, v[142:143]
	global_load_dword v166, v[144:145], off
	global_load_dword v167, v[8:9], off offset:24
	s_waitcnt vmcnt(0)
	v_cndmask_b32_e64 v20, 0, 1, s[30:31]
	v_mov_b32_e32 v18, 1.0
	v_cmp_ne_u32_e64 s[34:35], 1, v20
	v_mov_b32_e32 v20, 1.0
	v_mul_f32_e32 v11, v152, v153
	ds_write_b32 v7, v11
	v_mul_f32_e32 v11, v154, v155
	ds_write_b32 v7, v11 offset:264
	v_mov_b32_e32 v11, 1.0
	v_mov_b32_e32 v19, 1.0
	v_mul_f32_e32 v18, v156, v157
	ds_write_b32 v7, v18 offset:528
	v_mul_f32_e32 v11, v158, v159
	ds_write_b32 v7, v11 offset:792
	v_mov_b32_e32 v11, 1.0
	v_mov_b32_e32 v19, 1.0
	v_mul_f32_e32 v18, v160, v161
	ds_write_b32 v7, v18 offset:1056
	v_mul_f32_e32 v11, v162, v163
	ds_write_b32 v7, v11 offset:1320
	v_mov_b32_e32 v11, 1.0
	v_mov_b32_e32 v19, 1.0
	v_mul_f32_e32 v18, v164, v165
	ds_write_b32 v7, v18 offset:1584
	v_mul_f32_e32 v10, v166, v167
	s_add_i32 s12, s12, 16
	ds_write_b32 v7, v10 offset:1848
	v_add_u32_e32 v7, 0x840, v7
	s_cmp_eq_u32 s12, 64
	v_lshl_add_u64 v[8:9], v[8:9], 0, 64
	s_cbranch_scc1 .LBB0_1735
	s_branch .LBB0_1738
.Lcvtga0_ng:
	v_add_u32_e32 v96, s12, v6
	v_ashrrev_i32_e32 v97, 31, v96
	v_lshlrev_b64 v[98:99], 11, v[96:97]
	v_lshl_add_u64 v[100:101], v[4:5], 0, v[98:99]
	global_load_dword v152, v[100:101], off
	v_add_u32_e32 v102, 2, v96
	v_ashrrev_i32_e32 v103, 31, v102
	v_lshlrev_b64 v[104:105], 11, v[102:103]
	v_lshl_add_u64 v[106:107], v[4:5], 0, v[104:105]
	global_load_dword v153, v[106:107], off
	v_add_u32_e32 v108, 4, v96
	v_ashrrev_i32_e32 v109, 31, v108
	v_lshlrev_b64 v[110:111], 11, v[108:109]
	v_lshl_add_u64 v[112:113], v[4:5], 0, v[110:111]
	global_load_dword v154, v[112:113], off
	v_add_u32_e32 v114, 6, v96
	v_ashrrev_i32_e32 v115, 31, v114
	v_lshlrev_b64 v[116:117], 11, v[114:115]
	v_lshl_add_u64 v[118:119], v[4:5], 0, v[116:117]
	global_load_dword v155, v[118:119], off
	v_add_u32_e32 v120, 8, v96
	v_ashrrev_i32_e32 v121, 31, v120
	v_lshlrev_b64 v[122:123], 11, v[120:121]
	v_lshl_add_u64 v[124:125], v[4:5], 0, v[122:123]
	global_load_dword v156, v[124:125], off
	v_add_u32_e32 v126, 10, v96
	v_ashrrev_i32_e32 v127, 31, v126
	v_lshlrev_b64 v[128:129], 11, v[126:127]
	v_lshl_add_u64 v[130:131], v[4:5], 0, v[128:129]
	global_load_dword v157, v[130:131], off
	v_add_u32_e32 v132, 12, v96
	v_ashrrev_i32_e32 v133, 31, v132
	v_lshlrev_b64 v[134:135], 11, v[132:133]
	v_lshl_add_u64 v[136:137], v[4:5], 0, v[134:135]
	global_load_dword v158, v[136:137], off
	v_add_u32_e32 v138, 14, v96
	v_ashrrev_i32_e32 v139, 31, v138
	v_lshlrev_b64 v[140:141], 11, v[138:139]
	v_lshl_add_u64 v[142:143], v[4:5], 0, v[140:141]
	global_load_dword v159, v[142:143], off
	s_waitcnt vmcnt(0)
	v_cndmask_b32_e64 v20, 0, 1, s[30:31]
	v_mov_b32_e32 v18, 1.0
	v_cmp_ne_u32_e64 s[34:35], 1, v20
	v_mov_b32_e32 v20, 1.0
	v_mul_f32_e32 v11, v152, v20
	ds_write_b32 v7, v11
	v_mul_f32_e32 v11, v153, v18
	ds_write_b32 v7, v11 offset:264
	v_mov_b32_e32 v11, 1.0
	v_mov_b32_e32 v19, 1.0
	v_mul_f32_e32 v18, v154, v19
	ds_write_b32 v7, v18 offset:528
	v_mul_f32_e32 v11, v155, v11
	ds_write_b32 v7, v11 offset:792
	v_mov_b32_e32 v11, 1.0
	v_mov_b32_e32 v19, 1.0
	v_mul_f32_e32 v18, v156, v19
	ds_write_b32 v7, v18 offset:1056
	v_mul_f32_e32 v11, v157, v11
	ds_write_b32 v7, v11 offset:1320
	v_mov_b32_e32 v11, 1.0
	v_mov_b32_e32 v19, 1.0
	v_mul_f32_e32 v18, v158, v19
	ds_write_b32 v7, v18 offset:1584
	v_mul_f32_e32 v10, v159, v11
	s_add_i32 s12, s12, 16
	ds_write_b32 v7, v10 offset:1848
	v_add_u32_e32 v7, 0x840, v7
	s_cmp_eq_u32 s12, 64
	v_lshl_add_u64 v[8:9], v[8:9], 0, 64
	s_cbranch_scc1 .LBB0_1735
	s_branch .LBB0_1738

; __device__ __forceinline__ void cvt_job(const Frame& F, const float* W, int K, int Nsrc, bf16_t* dst, int nrows, int mode, float scale, const float* gain = nullptr) {
;     ...
;     for (int it = F.gw; it < nitems; it += F.NGW) {
;         const int kb = it / nblk, nb = it % nblk, k0 = 64 * kb, n0 = 32 * nb;
;         const int nsrc = map_col(mode, n0 + (lane & 31));
; #pragma unroll 8
;         for (int i = 0; i < 32; ++i) { const int kk = 2 * i + (lane >> 5); scr[kk * 33 + (lane & 31)] = (mode == MAP_ZERO) ? 0.f : W[(size_t)(k0 + kk) * Nsrc + nsrc] * (gain ? scale * gain[k0 + kk] : scale); }
.LBB0_1759:
	s_andn2_b64 vcc, exec, s[30:31]
	s_cbranch_vccnz .Lcvtga1_ng
	v_add_u32_e32 v96, s12, v6
	v_mad_i64_i32 v[98:99], s[34:35], v96, s8, v[4:5]
	global_load_dword v152, v[98:99], off
	v_ashrrev_i32_e32 v97, 31, v96
	v_lshl_add_u64 v[100:101], v[96:97], 2, s[40:41]
	global_load_dword v153, v[100:101], off
	v_add_u32_e32 v103, 2, v96
	v_mad_i64_i32 v[104:105], s[46:47], v103, s8, v[4:5]
	global_load_dword v154, v[104:105], off
	global_load_dword v155, v[8:9], off offset:-24
	v_add_u32_e32 v107, 4, v96
	v_mad_i64_i32 v[108:109], s[46:47], v107, s8, v[4:5]
	global_load_dword v156, v[108:109], off
	global_load_dword v157, v[8:9], off offset:-16
	v_add_u32_e32 v110, 6, v96
	v_mad_i64_i32 v[112:113], s[46:47], v110, s8, v[4:5]
	global_load_dword v158, v[112:113], off
	global_load_dword v159, v[8:9], off offset:-8
	v_add_u32_e32 v115, 8, v96
	v_mad_i64_i32 v[116:117], s[46:47], v115, s8, v[4:5]
	global_load_dword v160, v[116:117], off
	global_load_dword v161, v[8:9], off
	v_add_u32_e32 v118, 10, v96
	v_mad_i64_i32 v[120:121], s[46:47], v118, s8, v[4:5]
	global_load_dword v162, v[120:121], off
	global_load_dword v163, v[8:9], off offset:8
	v_add_u32_e32 v123, 12, v96
	v_mad_i64_i32 v[124:125], s[46:47], v123, s8, v[4:5]
	global_load_dword v164, v[124:125], off
	global_load_dword v165, v[8:9], off offset:16
	v_add_u32_e32 v126, 14, v96
	v_mad_i64_i32 v[128:129], s[46:47], v126, s8, v[4:5]
	global_load_dword v166, v[128:129], off
	global_load_dword v167, v[8:9], off offset:24
	s_waitcnt vmcnt(0)
	v_cndmask_b32_e64 v20, 0, 1, s[30:31]
	v_mov_b32_e32 v18, 1.0
	v_cmp_ne_u32_e64 s[34:35], 1, v20
	v_mov_b32_e32 v20, 1.0
	v_mul_f32_e32 v11, v152, v153
	ds_write_b32 v7, v11
	v_mul_f32_e32 v11, v154, v155
	ds_write_b32 v7, v11 offset:264
	v_mov_b32_e32 v11, 1.0
	v_mov_b32_e32 v19, 1.0
	v_mul_f32_e32 v18, v156, v157
	ds_write_b32 v7, v18 offset:528
	v_mul_f32_e32 v11, v158, v159
	ds_write_b32 v7, v11 offset:792
	v_mov_b32_e32 v11, 1.0
	v_mov_b32_e32 v19, 1.0
	v_mul_f32_e32 v18, v160, v161
	ds_write_b32 v7, v18 offset:1056
	v_mul_f32_e32 v11, v162, v163
	ds_write_b32 v7, v11 offset:1320
	v_mov_b32_e32 v11, 1.0
	v_mov_b32_e32 v19, 1.0
	v_mul_f32_e32 v18, v164, v165
	ds_write_b32 v7, v18 offset:1584
	v_mul_f32_e32 v10, v166, v167
	s_add_i32 s12, s12, 16
	ds_write_b32 v7, v10 offset:1848
	v_add_u32_e32 v7, 0x840, v7
	s_cmp_eq_u32 s12, 64
	v_lshl_add_u64 v[8:9], v[8:9], 0, 64
	s_cbranch_scc1 .LBB0_1756
	s_branch .LBB0_1759
.Lcvtga1_ng:
	v_add_u32_e32 v96, s12, v6
	v_mad_i64_i32 v[98:99], s[34:35], v96, s8, v[4:5]
	global_load_dword v152, v[98:99], off
	v_add_u32_e32 v97, 2, v96
	v_mad_i64_i32 v[100:101], s[46:47], v97, s8, v[4:5]
	global_load_dword v153, v[100:101], off
	v_add_u32_e32 v103, 4, v96
	v_mad_i64_i32 v[104:105], s[46:47], v103, s8, v[4:5]
	global_load_dword v154, v[104:105], off
	v_add_u32_e32 v106, 6, v96
	v_mad_i64_i32 v[108:109], s[46:47], v106, s8, v[4:5]
	global_load_dword v155, v[108:109], off
	v_add_u32_e32 v111, 8, v96
	v_mad_i64_i32 v[112:113], s[46:47], v111, s8, v[4:5]
	global_load_dword v156, v[112:113], off
	v_add_u32_e32 v114, 10, v96
	v_mad_i64_i32 v[116:117], s[46:47], v114, s8, v[4:5]
	global_load_dword v157, v[116:117], off
	v_add_u32_e32 v119, 12, v96
	v_mad_i64_i32 v[120:121], s[46:47], v119, s8, v[4:5]
	global_load_dword v158, v[120:121], off
	v_add_u32_e32 v122, 14, v96
	v_mad_i64_i32 v[124:125], s[46:47], v122, s8, v[4:5]
	global_load_dword v159, v[124:125], off
	s_waitcnt vmcnt(0)
	v_cndmask_b32_e64 v20, 0, 1, s[30:31]
	v_ashrrev_i32_e32 v11, 31, v96
	v_mov_b32_e32 v18, 1.0
	v_cmp_ne_u32_e64 s[34:35], 1, v20
	v_mov_b32_e32 v20, 1.0
	v_mul_f32_e32 v11, v152, v20
	ds_write_b32 v7, v11
	v_mul_f32_e32 v11, v153, v18
	ds_write_b32 v7, v11 offset:264
	v_mov_b32_e32 v11, 1.0
	v_mov_b32_e32 v19, 1.0
	v_mul_f32_e32 v18, v154, v19
	ds_write_b32 v7, v18 offset:528
	v_mul_f32_e32 v11, v155, v11
	ds_write_b32 v7, v11 offset:792
	v_mov_b32_e32 v11, 1.0
	v_mov_b32_e32 v19, 1.0
	v_mul_f32_e32 v18, v156, v19
	ds_write_b32 v7, v18 offset:1056
	v_mul_f32_e32 v11, v157, v11
	ds_write_b32 v7, v11 offset:1320
	v_mov_b32_e32 v11, 1.0
	v_mov_b32_e32 v19, 1.0
	v_mul_f32_e32 v18, v158, v19
	ds_write_b32 v7, v18 offset:1584
	v_mul_f32_e32 v10, v159, v11
	s_add_i32 s12, s12, 16
	ds_write_b32 v7, v10 offset:1848
	v_add_u32_e32 v7, 0x840, v7
	s_cmp_eq_u32 s12, 64
	v_lshl_add_u64 v[8:9], v[8:9], 0, 64
	s_cbranch_scc1 .LBB0_1756
	s_branch .LBB0_1759
